# v082 + the seven GEMM loop heads and the attention loop head aligned to 64-byte instruction-fetch lines
# speedup vs baseline: 1.0058x; 1.0058x over previous
;     __device__ bool next(int i, Unit& u) const { if (!b.next(i / 3, u)) return false; u.pz = i % 3; return true; }
; template <class Epi, class Sched>
; __device__ __forceinline__ void gemm_phase(LAS unsigned char* lds, const int tid, const Gemm g, const Sched& S, const Epi& E) {
;     ...
;         const bool has_next = S.next(ui + 1, nxt);
;         const gchar* nA = has_next ? (const gchar*)g.A + (size_t)nxt.pm * tstep + (size_t)nxt.pz * g.zA : cA;
;         const gchar* nB = has_next ? (const gchar*)g.Bt + (size_t)nxt.pn * tstep + (size_t)nxt.pz * g.zB : cB;
;         for (int t = 0; t < nt; t += 2) {
;             const bool last = (t == nt - 2);
;             const gchar* a1 = cA + (size_t)(t + 1) * kstep;
;             const gchar* a2 = last ? nA : cA + (size_t)(t + 2) * kstep; const gchar* b2 = last ? nB : cB + (size_t)(t + 2) * kstep;
;             const gchar* a3 = a2 + kstep; const gchar* b3 = b2 + kstep;
;     ...
; #pragma unroll
;         for (int a = 0; a < 2; ++a)
; #pragma unroll
;             for (int b = 0; b < 2; ++b)
; #pragma unroll
;                 for (int m = 0; m < 4; ++m)
; #pragma unroll
;                     for (int n = 0; n < 2; ++n) acc[a][b][m][n] = (f32x4){0.f, 0.f, 0.f, 0.f};
;         cur = nxt; cA = nA; cB = nB; ++ui;
.LBB0_318:
	s_add_u32 s31, s72, 0x100
	v_mov_b32_e32 v2, 0
	s_addc_u32 s93, s73, 0
	s_mov_b32 s29, -2
	v_mov_b32_e32 v3, v2
	v_mov_b32_e32 v4, v2
	v_mov_b32_e32 v5, v2
	v_mov_b32_e32 v6, v2
	v_mov_b32_e32 v7, v2
	v_mov_b32_e32 v8, v2
	v_mov_b32_e32 v9, v2
	v_mov_b32_e32 v18, v2
	v_mov_b32_e32 v19, v2
	v_mov_b32_e32 v20, v2
	v_mov_b32_e32 v21, v2
	v_mov_b32_e32 v22, v2
	v_mov_b32_e32 v23, v2
	v_mov_b32_e32 v24, v2
	v_mov_b32_e32 v25, v2
	v_mov_b32_e32 v34, v2
	v_mov_b32_e32 v35, v2
	v_mov_b32_e32 v36, v2
	v_mov_b32_e32 v37, v2
	v_mov_b32_e32 v38, v2
	v_mov_b32_e32 v39, v2
	v_mov_b32_e32 v40, v2
	v_mov_b32_e32 v41, v2
	v_mov_b32_e32 v50, v2
	v_mov_b32_e32 v51, v2
	v_mov_b32_e32 v52, v2
	v_mov_b32_e32 v53, v2
	v_mov_b32_e32 v54, v2
	v_mov_b32_e32 v55, v2
	v_mov_b32_e32 v56, v2
	v_mov_b32_e32 v57, v2
	v_mov_b32_e32 v10, v2
	v_mov_b32_e32 v11, v2
	v_mov_b32_e32 v12, v2
	v_mov_b32_e32 v13, v2
	v_mov_b32_e32 v14, v2
	v_mov_b32_e32 v15, v2
	v_mov_b32_e32 v16, v2
	v_mov_b32_e32 v17, v2
	v_mov_b32_e32 v26, v2
	v_mov_b32_e32 v27, v2
	v_mov_b32_e32 v28, v2
	v_mov_b32_e32 v29, v2
	v_mov_b32_e32 v30, v2
	v_mov_b32_e32 v31, v2
	v_mov_b32_e32 v32, v2
	v_mov_b32_e32 v33, v2
	v_mov_b32_e32 v42, v2
	v_mov_b32_e32 v43, v2
	v_mov_b32_e32 v44, v2
	v_mov_b32_e32 v45, v2
	v_mov_b32_e32 v46, v2
	v_mov_b32_e32 v47, v2
	v_mov_b32_e32 v48, v2
	v_mov_b32_e32 v49, v2
	v_mov_b32_e32 v58, v2
	v_mov_b32_e32 v59, v2
	v_mov_b32_e32 v60, v2
	v_mov_b32_e32 v61, v2
	v_mov_b32_e32 v62, v2
	v_mov_b32_e32 v63, v2
	v_mov_b32_e32 v64, v2
	v_mov_b32_e32 v65, v2
	v_mov_b32_e32 v66, v2
	v_mov_b32_e32 v67, v2
	v_mov_b32_e32 v68, v2
	v_mov_b32_e32 v69, v2
	v_mov_b32_e32 v70, v2
	v_mov_b32_e32 v71, v2
	v_mov_b32_e32 v72, v2
	v_mov_b32_e32 v73, v2
	s_waitcnt vmcnt(0)
	v_mov_b32_e32 v82, v2
	v_mov_b32_e32 v83, v2
	v_mov_b32_e32 v84, v2
	v_mov_b32_e32 v85, v2
	v_mov_b32_e32 v86, v2
	v_mov_b32_e32 v87, v2
	v_mov_b32_e32 v88, v2
	v_mov_b32_e32 v89, v2
	v_mov_b32_e32 v98, v2
	v_mov_b32_e32 v99, v2
	v_mov_b32_e32 v100, v2
	v_mov_b32_e32 v101, v2
	v_mov_b32_e32 v102, v2
	v_mov_b32_e32 v103, v2
	v_mov_b32_e32 v104, v2
	v_mov_b32_e32 v105, v2
	v_mov_b32_e32 v114, v2
	v_mov_b32_e32 v115, v2
	v_mov_b32_e32 v116, v2
	v_mov_b32_e32 v117, v2
	v_mov_b32_e32 v118, v2
	v_mov_b32_e32 v119, v2
	v_mov_b32_e32 v120, v2
	v_mov_b32_e32 v121, v2
	v_mov_b32_e32 v74, v2
	v_mov_b32_e32 v75, v2
	v_mov_b32_e32 v76, v2
	v_mov_b32_e32 v77, v2
	v_mov_b32_e32 v78, v2
	v_mov_b32_e32 v79, v2
	v_mov_b32_e32 v80, v2
	v_mov_b32_e32 v81, v2
	v_mov_b32_e32 v90, v2
	v_mov_b32_e32 v91, v2
	v_mov_b32_e32 v92, v2
	v_mov_b32_e32 v93, v2
	v_mov_b32_e32 v94, v2
	v_mov_b32_e32 v95, v2
	v_mov_b32_e32 v96, v2
	v_mov_b32_e32 v97, v2
	v_mov_b32_e32 v106, v2
	v_mov_b32_e32 v107, v2
	v_mov_b32_e32 v108, v2
	v_mov_b32_e32 v109, v2
	v_mov_b32_e32 v110, v2
	v_mov_b32_e32 v111, v2
	v_mov_b32_e32 v112, v2
	v_mov_b32_e32 v113, v2
	v_mov_b32_e32 v122, v2
	v_mov_b32_e32 v123, v2
	v_mov_b32_e32 v124, v2
	v_mov_b32_e32 v125, v2
	v_mov_b32_e32 v126, v2
	v_mov_b32_e32 v127, v2
	v_mov_b32_e32 v128, v2
	v_mov_b32_e32 v129, v2
	v_add_u32_e32 v201, 0x80, v0
	v_add_u32_e32 v247, 0x80, v158
	v_add_u32_e32 v249, 0x80, v154
	v_add_u32_e32 v251, 0x80, v156
	.p2align	6

;     __device__ bool next(int i, Unit& u) const { if (!b.next(i / 3, u)) return false; u.pz = i % 3; return true; }
; template <class Epi, class Sched>
; __device__ __forceinline__ void gemm_phase(LAS unsigned char* lds, const int tid, const Gemm g, const Sched& S, const Epi& E) {
;     ...
;         const bool has_next = S.next(ui + 1, nxt);
;         const gchar* nA = has_next ? (const gchar*)g.A + (size_t)nxt.pm * tstep + (size_t)nxt.pz * g.zA : cA;
;         const gchar* nB = has_next ? (const gchar*)g.Bt + (size_t)nxt.pn * tstep + (size_t)nxt.pz * g.zB : cB;
;         for (int t = 0; t < nt; t += 2) {
;             const bool last = (t == nt - 2);
;             const gchar* a1 = cA + (size_t)(t + 1) * kstep;
;             const gchar* a2 = last ? nA : cA + (size_t)(t + 2) * kstep; const gchar* b2 = last ? nB : cB + (size_t)(t + 2) * kstep;
;             const gchar* a3 = a2 + kstep; const gchar* b3 = b2 + kstep;
;     ...
; #pragma unroll
;         for (int a = 0; a < 2; ++a)
; #pragma unroll
;             for (int b = 0; b < 2; ++b)
; #pragma unroll
;                 for (int m = 0; m < 4; ++m)
; #pragma unroll
;                     for (int n = 0; n < 2; ++n) acc[a][b][m][n] = (f32x4){0.f, 0.f, 0.f, 0.f};
;         cur = nxt; cA = nA; cB = nB; ++ui;
.LBB0_368:
	s_ashr_i32 s11, s10, 31
	s_lshl_b64 s[46:47], s[10:11], 19
	s_add_u32 s60, s86, s46
	s_addc_u32 s61, s87, s47
	s_and_b64 s[46:47], s[2:3], exec
	s_cselect_b32 s11, s61, s21
	s_cselect_b32 s12, s60, s20
	s_ashr_i32 s9, s8, 31
	s_lshl_b64 s[46:47], s[8:9], 19
	s_add_u32 s62, s58, s46
	s_addc_u32 s63, s59, s47
	s_and_b64 s[46:47], s[2:3], exec
	s_cselect_b32 s9, s63, s17
	s_cselect_b32 s15, s62, s16
	s_add_u32 s23, s16, 0x100
	s_addc_u32 s24, s17, 0
	s_add_u32 s16, s20, 0x40080
	v_mov_b32_e32 v2, 0
	s_addc_u32 s17, s21, 0
	s_mov_b32 s31, -2
	v_mov_b32_e32 v3, v2
	v_mov_b32_e32 v4, v2
	v_mov_b32_e32 v5, v2
	v_mov_b32_e32 v10, v2
	v_mov_b32_e32 v11, v2
	v_mov_b32_e32 v12, v2
	v_mov_b32_e32 v13, v2
	v_mov_b32_e32 v18, v2
	v_mov_b32_e32 v19, v2
	v_mov_b32_e32 v20, v2
	v_mov_b32_e32 v21, v2
	v_mov_b32_e32 v26, v2
	v_mov_b32_e32 v27, v2
	v_mov_b32_e32 v28, v2
	v_mov_b32_e32 v29, v2
	v_mov_b32_e32 v34, v2
	v_mov_b32_e32 v35, v2
	v_mov_b32_e32 v36, v2
	v_mov_b32_e32 v37, v2
	v_mov_b32_e32 v42, v2
	v_mov_b32_e32 v43, v2
	v_mov_b32_e32 v44, v2
	v_mov_b32_e32 v45, v2
	v_mov_b32_e32 v50, v2
	v_mov_b32_e32 v51, v2
	v_mov_b32_e32 v52, v2
	v_mov_b32_e32 v53, v2
	v_mov_b32_e32 v58, v2
	v_mov_b32_e32 v59, v2
	v_mov_b32_e32 v60, v2
	v_mov_b32_e32 v61, v2
	v_mov_b32_e32 v6, v2
	v_mov_b32_e32 v7, v2
	v_mov_b32_e32 v8, v2
	v_mov_b32_e32 v9, v2
	v_mov_b32_e32 v14, v2
	v_mov_b32_e32 v15, v2
	v_mov_b32_e32 v16, v2
	v_mov_b32_e32 v17, v2
	v_mov_b32_e32 v22, v2
	v_mov_b32_e32 v23, v2
	v_mov_b32_e32 v24, v2
	v_mov_b32_e32 v25, v2
	v_mov_b32_e32 v30, v2
	v_mov_b32_e32 v31, v2
	v_mov_b32_e32 v32, v2
	v_mov_b32_e32 v33, v2
	v_mov_b32_e32 v38, v2
	v_mov_b32_e32 v39, v2
	v_mov_b32_e32 v40, v2
	v_mov_b32_e32 v41, v2
	v_mov_b32_e32 v46, v2
	v_mov_b32_e32 v47, v2
	v_mov_b32_e32 v48, v2
	v_mov_b32_e32 v49, v2
	v_mov_b32_e32 v54, v2
	v_mov_b32_e32 v55, v2
	v_mov_b32_e32 v56, v2
	v_mov_b32_e32 v57, v2
	v_mov_b32_e32 v62, v2
	v_mov_b32_e32 v63, v2
	v_mov_b32_e32 v64, v2
	v_mov_b32_e32 v65, v2
	v_mov_b32_e32 v66, v2
	v_mov_b32_e32 v67, v2
	v_mov_b32_e32 v68, v2
	v_mov_b32_e32 v69, v2
	v_mov_b32_e32 v74, v2
	v_mov_b32_e32 v75, v2
	v_mov_b32_e32 v76, v2
	v_mov_b32_e32 v77, v2
	s_waitcnt vmcnt(0)
	v_mov_b32_e32 v82, v2
	v_mov_b32_e32 v83, v2
	v_mov_b32_e32 v84, v2
	v_mov_b32_e32 v85, v2
	v_mov_b32_e32 v90, v2
	v_mov_b32_e32 v91, v2
	v_mov_b32_e32 v92, v2
	v_mov_b32_e32 v93, v2
	v_mov_b32_e32 v98, v2
	v_mov_b32_e32 v99, v2
	v_mov_b32_e32 v100, v2
	v_mov_b32_e32 v101, v2
	v_mov_b32_e32 v106, v2
	v_mov_b32_e32 v107, v2
	v_mov_b32_e32 v108, v2
	v_mov_b32_e32 v109, v2
	v_mov_b32_e32 v114, v2
	v_mov_b32_e32 v115, v2
	v_mov_b32_e32 v116, v2
	v_mov_b32_e32 v117, v2
	v_mov_b32_e32 v122, v2
	v_mov_b32_e32 v123, v2
	v_mov_b32_e32 v124, v2
	v_mov_b32_e32 v125, v2
	v_mov_b32_e32 v70, v2
	v_mov_b32_e32 v71, v2
	v_mov_b32_e32 v72, v2
	v_mov_b32_e32 v73, v2
	v_mov_b32_e32 v78, v2
	v_mov_b32_e32 v79, v2
	v_mov_b32_e32 v80, v2
	v_mov_b32_e32 v81, v2
	v_mov_b32_e32 v86, v2
	v_mov_b32_e32 v87, v2
	v_mov_b32_e32 v88, v2
	v_mov_b32_e32 v89, v2
	v_mov_b32_e32 v94, v2
	v_mov_b32_e32 v95, v2
	v_mov_b32_e32 v96, v2
	v_mov_b32_e32 v97, v2
	v_mov_b32_e32 v102, v2
	v_mov_b32_e32 v103, v2
	v_mov_b32_e32 v104, v2
	v_mov_b32_e32 v105, v2
	v_mov_b32_e32 v110, v2
	v_mov_b32_e32 v111, v2
	v_mov_b32_e32 v112, v2
	v_mov_b32_e32 v113, v2
	v_mov_b32_e32 v118, v2
	v_mov_b32_e32 v119, v2
	v_mov_b32_e32 v120, v2
	v_mov_b32_e32 v121, v2
	v_mov_b32_e32 v126, v2
	v_mov_b32_e32 v127, v2
	v_mov_b32_e32 v128, v2
	v_mov_b32_e32 v129, v2
	v_add_u32_e32 v141, 0x80, v0
	v_add_u32_e32 v153, 0x80, v130
	v_add_u32_e32 v201, 0x80, v134
	v_add_u32_e32 v225, 0x80, v132
	.p2align	6

;     __device__ bool next(int i, Unit& u) const { if (!b.next(i / 3, u)) return false; u.pz = i % 3; return true; }
; template <class Epi, class Sched>
; __device__ __forceinline__ void gemm_phase(LAS unsigned char* lds, const int tid, const Gemm g, const Sched& S, const Epi& E) {
;     ...
;         const bool has_next = S.next(ui + 1, nxt);
;         const gchar* nA = has_next ? (const gchar*)g.A + (size_t)nxt.pm * tstep + (size_t)nxt.pz * g.zA : cA;
;         const gchar* nB = has_next ? (const gchar*)g.Bt + (size_t)nxt.pn * tstep + (size_t)nxt.pz * g.zB : cB;
;         for (int t = 0; t < nt; t += 2) {
;             const bool last = (t == nt - 2);
;             const gchar* a1 = cA + (size_t)(t + 1) * kstep;
;             const gchar* a2 = last ? nA : cA + (size_t)(t + 2) * kstep; const gchar* b2 = last ? nB : cB + (size_t)(t + 2) * kstep;
;             const gchar* a3 = a2 + kstep; const gchar* b3 = b2 + kstep;
;     ...
; #pragma unroll
;         for (int a = 0; a < 2; ++a)
; #pragma unroll
;             for (int b = 0; b < 2; ++b)
; #pragma unroll
;                 for (int m = 0; m < 4; ++m)
; #pragma unroll
;                     for (int n = 0; n < 2; ++n) acc[a][b][m][n] = (f32x4){0.f, 0.f, 0.f, 0.f};
;         cur = nxt; cA = nA; cB = nB; ++ui;
.LBB0_396:
	s_ashr_i32 s57, s56, 31
	s_lshl_b64 s[50:51], s[56:57], 19
	s_add_u32 s58, s64, s50
	s_addc_u32 s59, s41, s51
	s_and_b64 s[50:51], s[6:7], exec
	s_cselect_b32 s1, s59, s93
	s_cselect_b32 s31, s58, s92
	s_ashr_i32 s17, s16, 31
	s_lshl_b64 s[50:51], s[16:17], 19
	s_add_u32 s60, s23, s50
	s_addc_u32 s61, s24, s51
	s_and_b64 s[50:51], s[6:7], exec
	s_cselect_b32 s17, s61, s21
	s_cselect_b32 s50, s60, s20
	s_add_u32 s51, s20, 0x100
	s_addc_u32 s52, s21, 0
	s_add_u32 s92, s92, 0x40080
	v_mov_b32_e32 v2, 0
	s_addc_u32 s93, s93, 0
	s_mov_b32 s53, -2
	s_waitcnt lgkmcnt(0)
	v_mov_b32_e32 v3, v2
	v_mov_b32_e32 v4, v2
	v_mov_b32_e32 v5, v2
	v_mov_b32_e32 v6, v2
	v_mov_b32_e32 v7, v2
	v_mov_b32_e32 v8, v2
	v_mov_b32_e32 v9, v2
	v_mov_b32_e32 v18, v2
	v_mov_b32_e32 v19, v2
	v_mov_b32_e32 v20, v2
	v_mov_b32_e32 v21, v2
	v_mov_b32_e32 v22, v2
	v_mov_b32_e32 v23, v2
	v_mov_b32_e32 v24, v2
	v_mov_b32_e32 v25, v2
	v_mov_b32_e32 v34, v2
	v_mov_b32_e32 v35, v2
	v_mov_b32_e32 v36, v2
	v_mov_b32_e32 v37, v2
	v_mov_b32_e32 v38, v2
	v_mov_b32_e32 v39, v2
	v_mov_b32_e32 v40, v2
	v_mov_b32_e32 v41, v2
	v_mov_b32_e32 v50, v2
	v_mov_b32_e32 v51, v2
	v_mov_b32_e32 v52, v2
	v_mov_b32_e32 v53, v2
	v_mov_b32_e32 v54, v2
	v_mov_b32_e32 v55, v2
	v_mov_b32_e32 v56, v2
	v_mov_b32_e32 v57, v2
	v_mov_b32_e32 v10, v2
	v_mov_b32_e32 v11, v2
	v_mov_b32_e32 v12, v2
	v_mov_b32_e32 v13, v2
	v_mov_b32_e32 v14, v2
	v_mov_b32_e32 v15, v2
	v_mov_b32_e32 v16, v2
	v_mov_b32_e32 v17, v2
	v_mov_b32_e32 v26, v2
	v_mov_b32_e32 v27, v2
	v_mov_b32_e32 v28, v2
	v_mov_b32_e32 v29, v2
	v_mov_b32_e32 v30, v2
	v_mov_b32_e32 v31, v2
	v_mov_b32_e32 v32, v2
	v_mov_b32_e32 v33, v2
	v_mov_b32_e32 v42, v2
	v_mov_b32_e32 v43, v2
	v_mov_b32_e32 v44, v2
	v_mov_b32_e32 v45, v2
	v_mov_b32_e32 v46, v2
	v_mov_b32_e32 v47, v2
	v_mov_b32_e32 v48, v2
	v_mov_b32_e32 v49, v2
	v_mov_b32_e32 v58, v2
	v_mov_b32_e32 v59, v2
	v_mov_b32_e32 v60, v2
	v_mov_b32_e32 v61, v2
	v_mov_b32_e32 v62, v2
	v_mov_b32_e32 v63, v2
	v_mov_b32_e32 v64, v2
	v_mov_b32_e32 v65, v2
	v_mov_b32_e32 v66, v2
	v_mov_b32_e32 v67, v2
	v_mov_b32_e32 v68, v2
	v_mov_b32_e32 v69, v2
	v_mov_b32_e32 v70, v2
	v_mov_b32_e32 v71, v2
	v_mov_b32_e32 v72, v2
	v_mov_b32_e32 v73, v2
	s_waitcnt vmcnt(0)
	v_mov_b32_e32 v82, v2
	v_mov_b32_e32 v83, v2
	v_mov_b32_e32 v84, v2
	v_mov_b32_e32 v85, v2
	v_mov_b32_e32 v86, v2
	v_mov_b32_e32 v87, v2
	v_mov_b32_e32 v88, v2
	v_mov_b32_e32 v89, v2
	v_mov_b32_e32 v98, v2
	v_mov_b32_e32 v99, v2
	v_mov_b32_e32 v100, v2
	v_mov_b32_e32 v101, v2
	v_mov_b32_e32 v102, v2
	v_mov_b32_e32 v103, v2
	v_mov_b32_e32 v104, v2
	v_mov_b32_e32 v105, v2
	v_mov_b32_e32 v114, v2
	v_mov_b32_e32 v115, v2
	v_mov_b32_e32 v116, v2
	v_mov_b32_e32 v117, v2
	v_mov_b32_e32 v118, v2
	v_mov_b32_e32 v119, v2
	v_mov_b32_e32 v120, v2
	v_mov_b32_e32 v121, v2
	v_mov_b32_e32 v74, v2
	v_mov_b32_e32 v75, v2
	v_mov_b32_e32 v76, v2
	v_mov_b32_e32 v77, v2
	v_mov_b32_e32 v78, v2
	v_mov_b32_e32 v79, v2
	v_mov_b32_e32 v80, v2
	v_mov_b32_e32 v81, v2
	v_mov_b32_e32 v90, v2
	v_mov_b32_e32 v91, v2
	v_mov_b32_e32 v92, v2
	v_mov_b32_e32 v93, v2
	v_mov_b32_e32 v94, v2
	v_mov_b32_e32 v95, v2
	v_mov_b32_e32 v96, v2
	v_mov_b32_e32 v97, v2
	v_mov_b32_e32 v106, v2
	v_mov_b32_e32 v107, v2
	v_mov_b32_e32 v108, v2
	v_mov_b32_e32 v109, v2
	v_mov_b32_e32 v110, v2
	v_mov_b32_e32 v111, v2
	v_mov_b32_e32 v112, v2
	v_mov_b32_e32 v113, v2
	v_mov_b32_e32 v122, v2
	v_mov_b32_e32 v123, v2
	v_mov_b32_e32 v124, v2
	v_mov_b32_e32 v125, v2
	v_mov_b32_e32 v126, v2
	v_mov_b32_e32 v127, v2
	v_mov_b32_e32 v128, v2
	v_mov_b32_e32 v129, v2
	v_add_u32_e32 v195, 0x80, v0
	v_add_u32_e32 v201, 0x80, v158
	v_add_u32_e32 v221, 0x80, v154
	v_add_u32_e32 v223, 0x80, v156
	.p2align	6

;     __device__ bool next(int i, Unit& u) const { if (!b.next(i / 3, u)) return false; u.pz = i % 3; return true; }
; template <class Epi, class Sched>
; __device__ __forceinline__ void gemm_phase(LAS unsigned char* lds, const int tid, const Gemm g, const Sched& S, const Epi& E) {
;     ...
;         const bool has_next = S.next(ui + 1, nxt);
;         const gchar* nA = has_next ? (const gchar*)g.A + (size_t)nxt.pm * tstep + (size_t)nxt.pz * g.zA : cA;
;         const gchar* nB = has_next ? (const gchar*)g.Bt + (size_t)nxt.pn * tstep + (size_t)nxt.pz * g.zB : cB;
;         for (int t = 0; t < nt; t += 2) {
;             const bool last = (t == nt - 2);
;             const gchar* a1 = cA + (size_t)(t + 1) * kstep;
;             const gchar* a2 = last ? nA : cA + (size_t)(t + 2) * kstep; const gchar* b2 = last ? nB : cB + (size_t)(t + 2) * kstep;
;             const gchar* a3 = a2 + kstep; const gchar* b3 = b2 + kstep;
;     ...
; #pragma unroll
;         for (int a = 0; a < 2; ++a)
; #pragma unroll
;             for (int b = 0; b < 2; ++b)
; #pragma unroll
;                 for (int m = 0; m < 4; ++m)
; #pragma unroll
;                     for (int n = 0; n < 2; ++n) acc[a][b][m][n] = (f32x4){0.f, 0.f, 0.f, 0.f};
;         cur = nxt; cA = nA; cB = nB; ++ui;
.LBB0_443:
	s_ashr_i32 s71, s70, 31
	s_lshl_b64 s[52:53], s[70:71], 18
	s_add_u32 s1, s74, s52
	s_addc_u32 s5, s75, s53
	s_ashr_i32 s63, s62, 31
	s_lshl_b64 s[52:53], s[62:63], 25
	s_add_u32 s56, s1, s52
	s_addc_u32 s57, s5, s53
	s_and_b64 s[52:53], s[2:3], exec
	s_cselect_b32 s1, s57, s21
	s_cselect_b32 s5, s56, s20
	s_ashr_i32 s61, s60, 31
	s_lshl_b64 s[52:53], s[60:61], 18
	s_add_u32 s15, s43, s52
	s_addc_u32 s23, s92, s53
	s_lshl_b64 s[52:53], s[62:63], 20
	s_add_u32 s58, s15, s52
	s_addc_u32 s59, s23, s53
	s_and_b64 s[52:53], s[2:3], exec
	s_cselect_b32 s15, s59, s17
	s_cselect_b32 s23, s58, s16
	s_add_u32 s24, s16, 0x100
	s_addc_u32 s31, s17, 0
	s_add_u32 s16, s20, 0x20080
	v_mov_b32_e32 v2, 0
	s_addc_u32 s17, s21, 0
	s_mov_b32 s51, -2
	v_mov_b32_e32 v3, v2
	v_mov_b32_e32 v4, v2
	v_mov_b32_e32 v5, v2
	v_mov_b32_e32 v6, v2
	v_mov_b32_e32 v7, v2
	v_mov_b32_e32 v8, v2
	v_mov_b32_e32 v9, v2
	v_mov_b32_e32 v18, v2
	v_mov_b32_e32 v19, v2
	v_mov_b32_e32 v20, v2
	v_mov_b32_e32 v21, v2
	v_mov_b32_e32 v22, v2
	v_mov_b32_e32 v23, v2
	v_mov_b32_e32 v24, v2
	v_mov_b32_e32 v25, v2
	v_mov_b32_e32 v34, v2
	v_mov_b32_e32 v35, v2
	v_mov_b32_e32 v36, v2
	v_mov_b32_e32 v37, v2
	v_mov_b32_e32 v38, v2
	v_mov_b32_e32 v39, v2
	v_mov_b32_e32 v40, v2
	v_mov_b32_e32 v41, v2
	v_mov_b32_e32 v50, v2
	v_mov_b32_e32 v51, v2
	v_mov_b32_e32 v52, v2
	v_mov_b32_e32 v53, v2
	v_mov_b32_e32 v54, v2
	v_mov_b32_e32 v55, v2
	v_mov_b32_e32 v56, v2
	v_mov_b32_e32 v57, v2
	v_mov_b32_e32 v10, v2
	v_mov_b32_e32 v11, v2
	v_mov_b32_e32 v12, v2
	v_mov_b32_e32 v13, v2
	v_mov_b32_e32 v14, v2
	v_mov_b32_e32 v15, v2
	v_mov_b32_e32 v16, v2
	v_mov_b32_e32 v17, v2
	v_mov_b32_e32 v26, v2
	v_mov_b32_e32 v27, v2
	v_mov_b32_e32 v28, v2
	v_mov_b32_e32 v29, v2
	v_mov_b32_e32 v30, v2
	v_mov_b32_e32 v31, v2
	v_mov_b32_e32 v32, v2
	v_mov_b32_e32 v33, v2
	v_mov_b32_e32 v42, v2
	v_mov_b32_e32 v43, v2
	v_mov_b32_e32 v44, v2
	v_mov_b32_e32 v45, v2
	v_mov_b32_e32 v46, v2
	v_mov_b32_e32 v47, v2
	v_mov_b32_e32 v48, v2
	v_mov_b32_e32 v49, v2
	v_mov_b32_e32 v58, v2
	v_mov_b32_e32 v59, v2
	v_mov_b32_e32 v60, v2
	v_mov_b32_e32 v61, v2
	v_mov_b32_e32 v62, v2
	v_mov_b32_e32 v63, v2
	v_mov_b32_e32 v64, v2
	v_mov_b32_e32 v65, v2
	v_mov_b32_e32 v66, v2
	v_mov_b32_e32 v67, v2
	v_mov_b32_e32 v68, v2
	v_mov_b32_e32 v69, v2
	v_mov_b32_e32 v70, v2
	v_mov_b32_e32 v71, v2
	v_mov_b32_e32 v72, v2
	v_mov_b32_e32 v73, v2
	s_waitcnt vmcnt(0)
	v_mov_b32_e32 v82, v2
	v_mov_b32_e32 v83, v2
	v_mov_b32_e32 v84, v2
	v_mov_b32_e32 v85, v2
	v_mov_b32_e32 v86, v2
	v_mov_b32_e32 v87, v2
	v_mov_b32_e32 v88, v2
	v_mov_b32_e32 v89, v2
	v_mov_b32_e32 v98, v2
	v_mov_b32_e32 v99, v2
	v_mov_b32_e32 v100, v2
	v_mov_b32_e32 v101, v2
	v_mov_b32_e32 v102, v2
	v_mov_b32_e32 v103, v2
	v_mov_b32_e32 v104, v2
	v_mov_b32_e32 v105, v2
	v_mov_b32_e32 v114, v2
	v_mov_b32_e32 v115, v2
	v_mov_b32_e32 v116, v2
	v_mov_b32_e32 v117, v2
	v_mov_b32_e32 v118, v2
	v_mov_b32_e32 v119, v2
	v_mov_b32_e32 v120, v2
	v_mov_b32_e32 v121, v2
	v_mov_b32_e32 v74, v2
	v_mov_b32_e32 v75, v2
	v_mov_b32_e32 v76, v2
	v_mov_b32_e32 v77, v2
	v_mov_b32_e32 v78, v2
	v_mov_b32_e32 v79, v2
	v_mov_b32_e32 v80, v2
	v_mov_b32_e32 v81, v2
	v_mov_b32_e32 v90, v2
	v_mov_b32_e32 v91, v2
	v_mov_b32_e32 v92, v2
	v_mov_b32_e32 v93, v2
	v_mov_b32_e32 v94, v2
	v_mov_b32_e32 v95, v2
	v_mov_b32_e32 v96, v2
	v_mov_b32_e32 v97, v2
	v_mov_b32_e32 v106, v2
	v_mov_b32_e32 v107, v2
	v_mov_b32_e32 v108, v2
	v_mov_b32_e32 v109, v2
	v_mov_b32_e32 v110, v2
	v_mov_b32_e32 v111, v2
	v_mov_b32_e32 v112, v2
	v_mov_b32_e32 v113, v2
	v_mov_b32_e32 v124, v2
	v_mov_b32_e32 v125, v2
	v_mov_b32_e32 v126, v2
	v_mov_b32_e32 v127, v2
	v_mov_b32_e32 v128, v2
	v_mov_b32_e32 v129, v2
	v_mov_b32_e32 v130, v2
	v_mov_b32_e32 v131, v2
	v_add_u32_e32 v201, 0x80, v0
	v_add_u32_e32 v215, 0x80, v208
	v_add_u32_e32 v217, 0x80, v204
	v_add_u32_e32 v219, 0x80, v206
	.p2align	6

.LBB0_496:
	v_ashrrev_i32_e32 v191, 31, v190
	v_lshlrev_b32_e32 v207, 2, v168
	s_waitcnt lgkmcnt(7)
	v_mfma_f32_32x32x16_bf16 v[66:81], v[162:165], v[130:133], v[34:49]
	v_exp_f32_e32 v65, v98
	v_exp_f32_e32 v162, v99
	s_nop 0
	v_cvt_pk_bf16_f32 v98, v65, v162
	v_add_f32_e32 v65, 0, v65
	v_add_f32_e32 v65, v162, v65
	s_waitcnt lgkmcnt(5)
	v_mfma_f32_32x32x16_bf16 v[34:49], v[158:161], v[130:133], v[34:49]
	v_exp_f32_e32 v158, v100
	v_exp_f32_e32 v159, v101
	v_add_f32_e32 v65, v158, v65
	v_cvt_pk_bf16_f32 v99, v158, v159
	v_add_f32_e32 v65, v159, v65
	v_mfma_f32_32x32x16_bf16 v[66:81], v[154:157], v[134:137], v[66:81]
	v_exp_f32_e32 v154, v102
	v_exp_f32_e32 v155, v103
	v_add_f32_e32 v65, v154, v65
	v_cvt_pk_bf16_f32 v100, v154, v155
	v_add_f32_e32 v65, v155, v65
	s_waitcnt lgkmcnt(3)
	v_mfma_f32_32x32x16_bf16 v[66:81], v[126:129], v[138:141], v[66:81]
	v_exp_f32_e32 v104, v104
	v_exp_f32_e32 v105, v105
	v_add_f32_e32 v65, v104, v65
	v_cvt_pk_bf16_f32 v101, v104, v105
	v_add_f32_e32 v65, v105, v65
	s_waitcnt lgkmcnt(2)
	v_mfma_f32_32x32x16_bf16 v[66:81], v[122:125], v[142:145], v[66:81]
	v_exp_f32_e32 v106, v106
	v_exp_f32_e32 v107, v107
	s_nop 0
	v_cvt_pk_bf16_f32 v102, v106, v107
	v_exp_f32_e32 v108, v108
	v_mfma_f32_32x32x16_bf16 v[34:49], v[60:63], v[134:137], v[34:49]
	v_exp_f32_e32 v109, v109
	v_add_f32_e32 v60, v106, v65
	v_add_f32_e32 v60, v107, v60
	v_add_f32_e32 v60, v108, v60
	v_cvt_pk_bf16_f32 v103, v108, v109
	v_exp_f32_e32 v110, v110
	v_exp_f32_e32 v111, v111
	s_waitcnt lgkmcnt(1)
	v_mfma_f32_32x32x16_bf16 v[34:49], v[56:59], v[138:141], v[34:49]
	v_add_f32_e32 v60, v109, v60
	v_add_f32_e32 v60, v110, v60
	v_cvt_pk_bf16_f32 v104, v110, v111
	v_exp_f32_e32 v112, v112
	v_exp_f32_e32 v162, v113
	v_add_f32_e32 v60, v111, v60
	v_add_f32_e32 v65, v112, v60
	v_cvt_pk_bf16_f32 v105, v112, v162
	s_setprio 0
	ds_read_b128 v[56:59], v64 offset:27648
	ds_read_b128 v[60:63], v64 offset:27680
	ds_read_b128 v[106:109], v64 offset:27712
	ds_read_b128 v[110:113], v64 offset:27744
	ds_read_b128 v[122:125], v64 offset:32256
	ds_read_b128 v[126:129], v64 offset:32288
	ds_read_b128 v[154:157], v64 offset:32320
	ds_read_b128 v[158:161], v64 offset:32352
	v_add_f32_e32 v64, v162, v65
	v_exp_f32_e32 v65, v82
	v_exp_f32_e32 v82, v83
	v_exp_f32_e32 v83, v84
	v_exp_f32_e32 v84, v85
	v_add_f32_e32 v64, v65, v64
	v_exp_f32_e32 v85, v86
	v_add_f32_e32 v64, v82, v64
	v_exp_f32_e32 v86, v87
	v_add_f32_e32 v64, v83, v64
	v_exp_f32_e32 v87, v88
	v_add_f32_e32 v64, v84, v64
	v_exp_f32_e32 v88, v89
	v_add_f32_e32 v64, v85, v64
	v_exp_f32_e32 v89, v90
	v_add_f32_e32 v64, v86, v64
	v_exp_f32_e32 v90, v91
	v_add_f32_e32 v64, v87, v64
	v_exp_f32_e32 v91, v92
	v_add_f32_e32 v64, v88, v64
	v_exp_f32_e32 v92, v93
	v_add_f32_e32 v64, v89, v64
	v_exp_f32_e32 v93, v94
	v_add_f32_e32 v64, v90, v64
	v_exp_f32_e32 v94, v95
	v_add_f32_e32 v64, v91, v64
	v_exp_f32_e32 v95, v96
	v_add_f32_e32 v64, v92, v64
	v_exp_f32_e32 v96, v97
	v_add_f32_e32 v64, v93, v64
	v_add_f32_e32 v64, v94, v64
	v_add_f32_e32 v64, v95, v64
	v_add_f32_e32 v64, v96, v64
	v_cvt_pk_bf16_f32 v82, v65, v82
	v_cvt_pk_bf16_f32 v83, v83, v84
	v_cvt_pk_bf16_f32 v84, v85, v86
	v_cvt_pk_bf16_f32 v85, v87, v88
	v_cvt_pk_bf16_f32 v86, v89, v90
	v_cvt_pk_bf16_f32 v87, v91, v92
	v_cvt_pk_bf16_f32 v88, v93, v94
	v_cvt_pk_bf16_f32 v89, v95, v96
	s_setprio 1
	s_waitcnt lgkmcnt(7)
	v_mfma_f32_32x32x16_bf16 v[18:33], v[56:59], v[98:101], v[18:33]
	v_add_f32_e32 v210, v50, v64
	s_waitcnt lgkmcnt(3)
	v_mfma_f32_32x32x16_bf16 v[2:17], v[122:125], v[98:101], v[2:17]
	v_mfma_f32_32x32x16_bf16 v[18:33], v[60:63], v[102:105], v[18:33]
	s_waitcnt lgkmcnt(2)
	v_mfma_f32_32x32x16_bf16 v[2:17], v[126:129], v[102:105], v[2:17]
	v_mfma_f32_32x32x16_bf16 v[18:33], v[106:109], v[82:85], v[18:33]
	s_waitcnt lgkmcnt(1)
	v_mfma_f32_32x32x16_bf16 v[2:17], v[154:157], v[82:85], v[2:17]
	v_mfma_f32_32x32x16_bf16 v[18:33], v[110:113], v[86:89], v[18:33]
	s_waitcnt lgkmcnt(0)
	v_mfma_f32_32x32x16_bf16 v[2:17], v[158:161], v[86:89], v[2:17]
	v_mfma_f32_32x32x16_bf16 v[34:49], v[52:55], v[142:145], v[34:49]
	s_setprio 0
	s_movk_i32 s2, 0x4800
	s_mov_b32 s3, 0
	s_mov_b32 s0, 0x9000
	s_mov_b32 s10, 6
	v_mov_b32_e32 v50, v51
	v_mov_b32_e32 v52, v51
	v_mov_b32_e32 v53, v51
	v_mov_b32_e32 v54, v51
	v_mov_b32_e32 v55, v51
	v_mov_b32_e32 v56, v51
	v_mov_b32_e32 v57, v51
	v_mov_b32_e32 v58, v51
	v_mov_b32_e32 v59, v51
	v_mov_b32_e32 v60, v51
	v_mov_b32_e32 v61, v51
	v_mov_b32_e32 v62, v51
	v_mov_b32_e32 v63, v51
	v_mov_b32_e32 v64, v51
	v_mov_b32_e32 v65, v51
	s_waitcnt vmcnt(3)
	ds_write_b128 v169, v[114:117]
	s_waitcnt vmcnt(2)
	ds_write_b128 v170, v[118:121] offset:9216
	v_readlane_b32 s1, v255, 20
	s_nop 3
	s_cmp_lt_u32 s1, 0x42400000
	s_cbranch_scc0 .Lattn_online_pre
	v_sub_f32_e32 v50, s1, v206
	v_exp_f32_e64 v52, -v50
	v_mov_b32_e32 v206, s1
	v_readfirstlane_b32 s3, v194
	v_readfirstlane_b32 s12, v195
	v_readfirstlane_b32 s15, v208
	v_readfirstlane_b32 s23, v209
	v_add_u32_e32 v248, 0x2400, v0
	v_pk_add_f32 v[66:67], v[66:67], v[50:51] op_sel_hi:[1,0] neg_lo:[0,1] neg_hi:[0,1]
	v_pk_add_f32 v[68:69], v[68:69], v[50:51] op_sel_hi:[1,0] neg_lo:[0,1] neg_hi:[0,1]
	v_pk_add_f32 v[70:71], v[70:71], v[50:51] op_sel_hi:[1,0] neg_lo:[0,1] neg_hi:[0,1]
	v_pk_add_f32 v[72:73], v[72:73], v[50:51] op_sel_hi:[1,0] neg_lo:[0,1] neg_hi:[0,1]
	v_pk_add_f32 v[74:75], v[74:75], v[50:51] op_sel_hi:[1,0] neg_lo:[0,1] neg_hi:[0,1]
	v_pk_add_f32 v[76:77], v[76:77], v[50:51] op_sel_hi:[1,0] neg_lo:[0,1] neg_hi:[0,1]
	v_pk_add_f32 v[78:79], v[78:79], v[50:51] op_sel_hi:[1,0] neg_lo:[0,1] neg_hi:[0,1]
	v_pk_add_f32 v[80:81], v[80:81], v[50:51] op_sel_hi:[1,0] neg_lo:[0,1] neg_hi:[0,1]
	v_pk_add_f32 v[34:35], v[34:35], v[50:51] op_sel_hi:[1,0] neg_lo:[0,1] neg_hi:[0,1]
	v_pk_add_f32 v[36:37], v[36:37], v[50:51] op_sel_hi:[1,0] neg_lo:[0,1] neg_hi:[0,1]
	v_pk_add_f32 v[38:39], v[38:39], v[50:51] op_sel_hi:[1,0] neg_lo:[0,1] neg_hi:[0,1]
	v_pk_add_f32 v[40:41], v[40:41], v[50:51] op_sel_hi:[1,0] neg_lo:[0,1] neg_hi:[0,1]
	v_pk_add_f32 v[42:43], v[42:43], v[50:51] op_sel_hi:[1,0] neg_lo:[0,1] neg_hi:[0,1]
	v_pk_add_f32 v[44:45], v[44:45], v[50:51] op_sel_hi:[1,0] neg_lo:[0,1] neg_hi:[0,1]
	v_pk_add_f32 v[46:47], v[46:47], v[50:51] op_sel_hi:[1,0] neg_lo:[0,1] neg_hi:[0,1]
	v_pk_add_f32 v[48:49], v[48:49], v[50:51] op_sel_hi:[1,0] neg_lo:[0,1] neg_hi:[0,1]
	v_subrev_u32_e32 v252, s3, v194
	v_subrev_u32_e32 v253, s15, v208
	v_pk_mul_f32 v[2:3], v[2:3], v[52:53] op_sel_hi:[1,0]
	v_pk_mul_f32 v[4:5], v[4:5], v[52:53] op_sel_hi:[1,0]
	v_pk_mul_f32 v[6:7], v[6:7], v[52:53] op_sel_hi:[1,0]
	v_pk_mul_f32 v[8:9], v[8:9], v[52:53] op_sel_hi:[1,0]
	v_pk_mul_f32 v[10:11], v[10:11], v[52:53] op_sel_hi:[1,0]
	v_pk_mul_f32 v[12:13], v[12:13], v[52:53] op_sel_hi:[1,0]
	v_pk_mul_f32 v[14:15], v[14:15], v[52:53] op_sel_hi:[1,0]
	v_pk_mul_f32 v[16:17], v[16:17], v[52:53] op_sel_hi:[1,0]
	v_pk_mul_f32 v[18:19], v[18:19], v[52:53] op_sel_hi:[1,0]
	v_pk_mul_f32 v[20:21], v[20:21], v[52:53] op_sel_hi:[1,0]
	v_pk_mul_f32 v[22:23], v[22:23], v[52:53] op_sel_hi:[1,0]
	v_pk_mul_f32 v[24:25], v[24:25], v[52:53] op_sel_hi:[1,0]
	v_pk_mul_f32 v[26:27], v[26:27], v[52:53] op_sel_hi:[1,0]
	v_pk_mul_f32 v[28:29], v[28:29], v[52:53] op_sel_hi:[1,0]
	v_pk_mul_f32 v[30:31], v[30:31], v[52:53] op_sel_hi:[1,0]
	v_pk_mul_f32 v[32:33], v[32:33], v[52:53] op_sel_hi:[1,0]
	v_mul_f32_e32 v210, v210, v52
	v_xor_b32_e32 v50, 0x80000000, v206
	v_mov_b32_e32 v51, v50
	v_mov_b32_e32 v52, v50
	v_mov_b32_e32 v53, v50
	v_mov_b32_e32 v54, v50
	v_mov_b32_e32 v55, v50
	v_mov_b32_e32 v56, v50
	v_mov_b32_e32 v57, v50
	v_mov_b32_e32 v58, v50
	v_mov_b32_e32 v59, v50
	v_mov_b32_e32 v60, v50
	v_mov_b32_e32 v61, v50
	v_mov_b32_e32 v62, v50
	v_mov_b32_e32 v63, v50
	v_mov_b32_e32 v64, v50
	v_mov_b32_e32 v65, v50
	s_waitcnt lgkmcnt(0)
	s_barrier
	ds_read_b128 v[162:165], v193
	ds_read_b128 v[178:181], v193 offset:4608
	ds_read_b128 v[166:169], v193 offset:32
	ds_read_b128 v[182:185], v193 offset:4640
	ds_read_b128 v[170:173], v193 offset:64
	ds_read_b128 v[186:189], v193 offset:4672
	ds_read_b128 v[174:177], v193 offset:96
	ds_read_b128 v[82:85], v193 offset:4704
	.p2align	6

;     __device__ bool next(int i, Unit& u) const { if (!b.next(i / 3, u)) return false; u.pz = i % 3; return true; }
; template <class Epi, class Sched>
; __device__ __forceinline__ void gemm_phase(LAS unsigned char* lds, const int tid, const Gemm g, const Sched& S, const Epi& E) {
;     ...
;         const bool has_next = S.next(ui + 1, nxt);
;         const gchar* nA = has_next ? (const gchar*)g.A + (size_t)nxt.pm * tstep + (size_t)nxt.pz * g.zA : cA;
;         const gchar* nB = has_next ? (const gchar*)g.Bt + (size_t)nxt.pn * tstep + (size_t)nxt.pz * g.zB : cB;
;         for (int t = 0; t < nt; t += 2) {
;             const bool last = (t == nt - 2);
;             const gchar* a1 = cA + (size_t)(t + 1) * kstep;
;             const gchar* a2 = last ? nA : cA + (size_t)(t + 2) * kstep; const gchar* b2 = last ? nB : cB + (size_t)(t + 2) * kstep;
;             const gchar* a3 = a2 + kstep; const gchar* b3 = b2 + kstep;
;     ...
; #pragma unroll
;         for (int a = 0; a < 2; ++a)
; #pragma unroll
;             for (int b = 0; b < 2; ++b)
; #pragma unroll
;                 for (int m = 0; m < 4; ++m)
; #pragma unroll
;                     for (int n = 0; n < 2; ++n) acc[a][b][m][n] = (f32x4){0.f, 0.f, 0.f, 0.f};
;         cur = nxt; cA = nA; cB = nB; ++ui;
.LBB0_558:
	s_ashr_i32 s9, s8, 31
	s_lshl_b64 s[16:17], s[8:9], 19
	s_add_u32 s16, s86, s16
	s_addc_u32 s17, s87, s17
	s_and_b64 s[42:43], s[2:3], exec
	s_cselect_b32 s9, s17, s61
	s_cselect_b32 s42, s16, s60
	s_ashr_i32 s7, s6, 31
	s_lshl_b64 s[44:45], s[6:7], 19
	s_add_u32 s56, s15, s44
	s_addc_u32 s57, s23, s45
	s_and_b64 s[44:45], s[2:3], exec
	s_cselect_b32 s7, s57, s21
	s_cselect_b32 s43, s56, s20
	s_add_u32 s44, s20, 0x100
	s_addc_u32 s45, s21, 0
	s_add_u32 s60, s60, 0x40080
	v_mov_b32_e32 v2, 0
	s_addc_u32 s61, s61, 0
	s_mov_b32 s46, -2
	v_mov_b32_e32 v3, v2
	v_mov_b32_e32 v4, v2
	v_mov_b32_e32 v5, v2
	v_mov_b32_e32 v6, v2
	v_mov_b32_e32 v7, v2
	v_mov_b32_e32 v8, v2
	v_mov_b32_e32 v9, v2
	v_mov_b32_e32 v10, v2
	v_mov_b32_e32 v11, v2
	v_mov_b32_e32 v12, v2
	v_mov_b32_e32 v13, v2
	v_mov_b32_e32 v18, v2
	v_mov_b32_e32 v19, v2
	v_mov_b32_e32 v20, v2
	v_mov_b32_e32 v21, v2
	v_mov_b32_e32 v26, v2
	v_mov_b32_e32 v27, v2
	v_mov_b32_e32 v28, v2
	v_mov_b32_e32 v29, v2
	v_mov_b32_e32 v34, v2
	v_mov_b32_e32 v35, v2
	v_mov_b32_e32 v36, v2
	v_mov_b32_e32 v37, v2
	v_mov_b32_e32 v42, v2
	v_mov_b32_e32 v43, v2
	v_mov_b32_e32 v44, v2
	v_mov_b32_e32 v45, v2
	v_mov_b32_e32 v50, v2
	v_mov_b32_e32 v51, v2
	v_mov_b32_e32 v52, v2
	v_mov_b32_e32 v53, v2
	v_mov_b32_e32 v14, v2
	v_mov_b32_e32 v15, v2
	v_mov_b32_e32 v16, v2
	v_mov_b32_e32 v17, v2
	v_mov_b32_e32 v22, v2
	v_mov_b32_e32 v23, v2
	v_mov_b32_e32 v24, v2
	v_mov_b32_e32 v25, v2
	v_mov_b32_e32 v30, v2
	v_mov_b32_e32 v31, v2
	v_mov_b32_e32 v32, v2
	v_mov_b32_e32 v33, v2
	v_mov_b32_e32 v38, v2
	v_mov_b32_e32 v39, v2
	v_mov_b32_e32 v40, v2
	v_mov_b32_e32 v41, v2
	v_mov_b32_e32 v46, v2
	v_mov_b32_e32 v47, v2
	v_mov_b32_e32 v48, v2
	v_mov_b32_e32 v49, v2
	v_mov_b32_e32 v54, v2
	v_mov_b32_e32 v55, v2
	v_mov_b32_e32 v56, v2
	v_mov_b32_e32 v57, v2
	v_mov_b32_e32 v58, v2
	v_mov_b32_e32 v59, v2
	v_mov_b32_e32 v60, v2
	v_mov_b32_e32 v61, v2
	v_mov_b32_e32 v62, v2
	v_mov_b32_e32 v63, v2
	v_mov_b32_e32 v64, v2
	v_mov_b32_e32 v65, v2
	v_mov_b32_e32 v66, v2
	v_mov_b32_e32 v67, v2
	v_mov_b32_e32 v68, v2
	v_mov_b32_e32 v69, v2
	v_mov_b32_e32 v70, v2
	v_mov_b32_e32 v71, v2
	v_mov_b32_e32 v72, v2
	v_mov_b32_e32 v73, v2
	v_mov_b32_e32 v74, v2
	v_mov_b32_e32 v75, v2
	v_mov_b32_e32 v76, v2
	v_mov_b32_e32 v77, v2
	s_waitcnt vmcnt(0)
	v_mov_b32_e32 v82, v2
	v_mov_b32_e32 v83, v2
	v_mov_b32_e32 v84, v2
	v_mov_b32_e32 v85, v2
	v_mov_b32_e32 v90, v2
	v_mov_b32_e32 v91, v2
	v_mov_b32_e32 v92, v2
	v_mov_b32_e32 v93, v2
	v_mov_b32_e32 v98, v2
	v_mov_b32_e32 v99, v2
	v_mov_b32_e32 v100, v2
	v_mov_b32_e32 v101, v2
	v_mov_b32_e32 v106, v2
	v_mov_b32_e32 v107, v2
	v_mov_b32_e32 v108, v2
	v_mov_b32_e32 v109, v2
	v_mov_b32_e32 v114, v2
	v_mov_b32_e32 v115, v2
	v_mov_b32_e32 v116, v2
	v_mov_b32_e32 v117, v2
	v_mov_b32_e32 v78, v2
	v_mov_b32_e32 v79, v2
	v_mov_b32_e32 v80, v2
	v_mov_b32_e32 v81, v2
	v_mov_b32_e32 v86, v2
	v_mov_b32_e32 v87, v2
	v_mov_b32_e32 v88, v2
	v_mov_b32_e32 v89, v2
	v_mov_b32_e32 v94, v2
	v_mov_b32_e32 v95, v2
	v_mov_b32_e32 v96, v2
	v_mov_b32_e32 v97, v2
	v_mov_b32_e32 v102, v2
	v_mov_b32_e32 v103, v2
	v_mov_b32_e32 v104, v2
	v_mov_b32_e32 v105, v2
	v_mov_b32_e32 v110, v2
	v_mov_b32_e32 v111, v2
	v_mov_b32_e32 v112, v2
	v_mov_b32_e32 v113, v2
	v_mov_b32_e32 v118, v2
	v_mov_b32_e32 v119, v2
	v_mov_b32_e32 v120, v2
	v_mov_b32_e32 v121, v2
	v_mov_b32_e32 v122, v2
	v_mov_b32_e32 v123, v2
	v_mov_b32_e32 v124, v2
	v_mov_b32_e32 v125, v2
	v_mov_b32_e32 v126, v2
	v_mov_b32_e32 v127, v2
	v_mov_b32_e32 v128, v2
	v_mov_b32_e32 v129, v2
	v_add_u32_e32 v161, 0x80, v0
	v_add_u32_e32 v195, 0x80, v134
	v_add_u32_e32 v201, 0x80, v138
	v_add_u32_e32 v227, 0x80, v136
	.p2align	6

; template <class Epi, class Sched>
; __device__ __forceinline__ void gemm_phase(LAS unsigned char* lds, const int tid, const Gemm g, const Sched& S, const Epi& E) {
;     ...
;             const gchar* a2 = last ? nA : cA + (size_t)(t + 2) * kstep; const gchar* b2 = last ? nB : cB + (size_t)(t + 2) * kstep;
;     ...
; #pragma unroll
;         for (int a = 0; a < 2; ++a)
; #pragma unroll
;             for (int b = 0; b < 2; ++b)
; #pragma unroll
;                 for (int m = 0; m < 4; ++m)
; #pragma unroll
;                     for (int n = 0; n < 2; ++n) acc[a][b][m][n] = (f32x4){0.f, 0.f, 0.f, 0.f};
;         cur = nxt; cA = nA; cB = nB; ++ui;
.LBB0_597:
	s_add_u32 s31, s20, 0x100
	v_mov_b32_e32 v2, 0
	s_addc_u32 s44, s21, 0
	s_mov_b32 s45, -2
	s_waitcnt lgkmcnt(0)
	v_mov_b32_e32 v3, v2
	v_mov_b32_e32 v4, v2
	v_mov_b32_e32 v5, v2
	v_mov_b32_e32 v6, v2
	v_mov_b32_e32 v7, v2
	v_mov_b32_e32 v8, v2
	v_mov_b32_e32 v9, v2
	v_mov_b32_e32 v18, v2
	v_mov_b32_e32 v19, v2
	v_mov_b32_e32 v20, v2
	v_mov_b32_e32 v21, v2
	v_mov_b32_e32 v22, v2
	v_mov_b32_e32 v23, v2
	v_mov_b32_e32 v24, v2
	v_mov_b32_e32 v25, v2
	v_mov_b32_e32 v34, v2
	v_mov_b32_e32 v35, v2
	v_mov_b32_e32 v36, v2
	v_mov_b32_e32 v37, v2
	v_mov_b32_e32 v38, v2
	v_mov_b32_e32 v39, v2
	v_mov_b32_e32 v40, v2
	v_mov_b32_e32 v41, v2
	v_mov_b32_e32 v50, v2
	v_mov_b32_e32 v51, v2
	v_mov_b32_e32 v52, v2
	v_mov_b32_e32 v53, v2
	v_mov_b32_e32 v54, v2
	v_mov_b32_e32 v55, v2
	v_mov_b32_e32 v56, v2
	v_mov_b32_e32 v57, v2
	v_mov_b32_e32 v10, v2
	v_mov_b32_e32 v11, v2
	v_mov_b32_e32 v12, v2
	v_mov_b32_e32 v13, v2
	v_mov_b32_e32 v14, v2
	v_mov_b32_e32 v15, v2
	v_mov_b32_e32 v16, v2
	v_mov_b32_e32 v17, v2
	v_mov_b32_e32 v26, v2
	v_mov_b32_e32 v27, v2
	v_mov_b32_e32 v28, v2
	v_mov_b32_e32 v29, v2
	v_mov_b32_e32 v30, v2
	v_mov_b32_e32 v31, v2
	v_mov_b32_e32 v32, v2
	v_mov_b32_e32 v33, v2
	v_mov_b32_e32 v42, v2
	v_mov_b32_e32 v43, v2
	v_mov_b32_e32 v44, v2
	v_mov_b32_e32 v45, v2
	v_mov_b32_e32 v46, v2
	v_mov_b32_e32 v47, v2
	v_mov_b32_e32 v48, v2
	v_mov_b32_e32 v49, v2
	v_mov_b32_e32 v58, v2
	v_mov_b32_e32 v59, v2
	v_mov_b32_e32 v60, v2
	v_mov_b32_e32 v61, v2
	v_mov_b32_e32 v62, v2
	v_mov_b32_e32 v63, v2
	v_mov_b32_e32 v64, v2
	v_mov_b32_e32 v65, v2
	v_mov_b32_e32 v66, v2
	v_mov_b32_e32 v67, v2
	v_mov_b32_e32 v68, v2
	v_mov_b32_e32 v69, v2
	v_mov_b32_e32 v70, v2
	v_mov_b32_e32 v71, v2
	v_mov_b32_e32 v72, v2
	v_mov_b32_e32 v73, v2
	s_waitcnt vmcnt(0)
	v_mov_b32_e32 v82, v2
	v_mov_b32_e32 v83, v2
	v_mov_b32_e32 v84, v2
	v_mov_b32_e32 v85, v2
	v_mov_b32_e32 v86, v2
	v_mov_b32_e32 v87, v2
	v_mov_b32_e32 v88, v2
	v_mov_b32_e32 v89, v2
	v_mov_b32_e32 v98, v2
	v_mov_b32_e32 v99, v2
	v_mov_b32_e32 v100, v2
	v_mov_b32_e32 v101, v2
	v_mov_b32_e32 v102, v2
	v_mov_b32_e32 v103, v2
	v_mov_b32_e32 v104, v2
	v_mov_b32_e32 v105, v2
	v_mov_b32_e32 v114, v2
	v_mov_b32_e32 v115, v2
	v_mov_b32_e32 v116, v2
	v_mov_b32_e32 v117, v2
	v_mov_b32_e32 v118, v2
	v_mov_b32_e32 v119, v2
	v_mov_b32_e32 v120, v2
	v_mov_b32_e32 v121, v2
	v_mov_b32_e32 v74, v2
	v_mov_b32_e32 v75, v2
	v_mov_b32_e32 v76, v2
	v_mov_b32_e32 v77, v2
	v_mov_b32_e32 v78, v2
	v_mov_b32_e32 v79, v2
	v_mov_b32_e32 v80, v2
	v_mov_b32_e32 v81, v2
	v_mov_b32_e32 v90, v2
	v_mov_b32_e32 v91, v2
	v_mov_b32_e32 v92, v2
	v_mov_b32_e32 v93, v2
	v_mov_b32_e32 v94, v2
	v_mov_b32_e32 v95, v2
	v_mov_b32_e32 v96, v2
	v_mov_b32_e32 v97, v2
	v_mov_b32_e32 v106, v2
	v_mov_b32_e32 v107, v2
	v_mov_b32_e32 v108, v2
	v_mov_b32_e32 v109, v2
	v_mov_b32_e32 v110, v2
	v_mov_b32_e32 v111, v2
	v_mov_b32_e32 v112, v2
	v_mov_b32_e32 v113, v2
	v_mov_b32_e32 v122, v2
	v_mov_b32_e32 v123, v2
	v_mov_b32_e32 v124, v2
	v_mov_b32_e32 v125, v2
	v_mov_b32_e32 v126, v2
	v_mov_b32_e32 v127, v2
	v_mov_b32_e32 v128, v2
	v_mov_b32_e32 v129, v2
	v_add_u32_e32 v221, 0x80, v0
	v_add_u32_e32 v223, 0x80, v182
	v_add_u32_e32 v225, 0x80, v178
	v_add_u32_e32 v227, 0x80, v180
	.p2align	6

;     __device__ bool next(int i, Unit& u) const { if (!b.next(i / 3, u)) return false; u.pz = i % 3; return true; }
; template <class Epi, class Sched>
; __device__ __forceinline__ void gemm_phase(LAS unsigned char* lds, const int tid, const Gemm g, const Sched& S, const Epi& E) {
;     ...
;         const bool has_next = S.next(ui + 1, nxt);
;         const gchar* nA = has_next ? (const gchar*)g.A + (size_t)nxt.pm * tstep + (size_t)nxt.pz * g.zA : cA;
;         const gchar* nB = has_next ? (const gchar*)g.Bt + (size_t)nxt.pn * tstep + (size_t)nxt.pz * g.zB : cB;
;         for (int t = 0; t < nt; t += 2) {
;             const bool last = (t == nt - 2);
;             const gchar* a1 = cA + (size_t)(t + 1) * kstep;
;             const gchar* a2 = last ? nA : cA + (size_t)(t + 2) * kstep; const gchar* b2 = last ? nB : cB + (size_t)(t + 2) * kstep;
;             const gchar* a3 = a2 + kstep; const gchar* b3 = b2 + kstep;
;     ...
; #pragma unroll
;         for (int a = 0; a < 2; ++a)
; #pragma unroll
;             for (int b = 0; b < 2; ++b)
; #pragma unroll
;                 for (int m = 0; m < 4; ++m)
; #pragma unroll
;                     for (int n = 0; n < 2; ++n) acc[a][b][m][n] = (f32x4){0.f, 0.f, 0.f, 0.f};
;         cur = nxt; cA = nA; cB = nB; ++ui;
.LBB0_646:
	s_ashr_i32 s9, s8, 31
	s_lshl_b64 s[10:11], s[8:9], 19
	s_add_u32 s10, s86, s10
	s_addc_u32 s11, s87, s11
	s_and_b64 s[16:17], s[2:3], exec
	s_cselect_b32 s9, s11, s59
	s_cselect_b32 s37, s10, s58
	s_ashr_i32 s7, s6, 31
	s_lshl_b64 s[16:17], s[6:7], 19
	s_add_u32 s16, s84, s16
	s_addc_u32 s17, s85, s17
	s_and_b64 s[38:39], s[2:3], exec
	s_cselect_b32 s7, s17, s21
	s_cselect_b32 s38, s16, s20
	s_add_u32 s39, s20, 0x100
	s_addc_u32 s40, s21, 0
	s_add_u32 s58, s58, 0x40080
	v_mov_b32_e32 v2, 0
	s_addc_u32 s59, s59, 0
	s_mov_b32 s41, -2
	v_mov_b32_e32 v3, v2
	v_mov_b32_e32 v4, v2
	v_mov_b32_e32 v5, v2
	v_mov_b32_e32 v6, v2
	v_mov_b32_e32 v7, v2
	v_mov_b32_e32 v8, v2
	v_mov_b32_e32 v9, v2
	v_mov_b32_e32 v18, v2
	v_mov_b32_e32 v19, v2
	v_mov_b32_e32 v20, v2
	v_mov_b32_e32 v21, v2
	v_mov_b32_e32 v22, v2
	v_mov_b32_e32 v23, v2
	v_mov_b32_e32 v24, v2
	v_mov_b32_e32 v25, v2
	v_mov_b32_e32 v34, v2
	v_mov_b32_e32 v35, v2
	v_mov_b32_e32 v36, v2
	v_mov_b32_e32 v37, v2
	v_mov_b32_e32 v38, v2
	v_mov_b32_e32 v39, v2
	v_mov_b32_e32 v40, v2
	v_mov_b32_e32 v41, v2
	v_mov_b32_e32 v50, v2
	v_mov_b32_e32 v51, v2
	v_mov_b32_e32 v52, v2
	v_mov_b32_e32 v53, v2
	v_mov_b32_e32 v54, v2
	v_mov_b32_e32 v55, v2
	v_mov_b32_e32 v56, v2
	v_mov_b32_e32 v57, v2
	v_mov_b32_e32 v10, v2
	v_mov_b32_e32 v11, v2
	v_mov_b32_e32 v12, v2
	v_mov_b32_e32 v13, v2
	v_mov_b32_e32 v14, v2
	v_mov_b32_e32 v15, v2
	v_mov_b32_e32 v16, v2
	v_mov_b32_e32 v17, v2
	v_mov_b32_e32 v26, v2
	v_mov_b32_e32 v27, v2
	v_mov_b32_e32 v28, v2
	v_mov_b32_e32 v29, v2
	v_mov_b32_e32 v30, v2
	v_mov_b32_e32 v31, v2
	v_mov_b32_e32 v32, v2
	v_mov_b32_e32 v33, v2
	v_mov_b32_e32 v42, v2
	v_mov_b32_e32 v43, v2
	v_mov_b32_e32 v44, v2
	v_mov_b32_e32 v45, v2
	v_mov_b32_e32 v46, v2
	v_mov_b32_e32 v47, v2
	v_mov_b32_e32 v48, v2
	v_mov_b32_e32 v49, v2
	v_mov_b32_e32 v58, v2
	v_mov_b32_e32 v59, v2
	v_mov_b32_e32 v60, v2
	v_mov_b32_e32 v61, v2
	v_mov_b32_e32 v62, v2
	v_mov_b32_e32 v63, v2
	v_mov_b32_e32 v64, v2
	v_mov_b32_e32 v65, v2
	v_mov_b32_e32 v66, v2
	v_mov_b32_e32 v67, v2
	v_mov_b32_e32 v68, v2
	v_mov_b32_e32 v69, v2
	v_mov_b32_e32 v70, v2
	v_mov_b32_e32 v71, v2
	v_mov_b32_e32 v72, v2
	v_mov_b32_e32 v73, v2
	v_mov_b32_e32 v82, v2
	v_mov_b32_e32 v83, v2
	v_mov_b32_e32 v84, v2
	v_mov_b32_e32 v85, v2
	v_mov_b32_e32 v86, v2
	v_mov_b32_e32 v87, v2
	v_mov_b32_e32 v88, v2
	v_mov_b32_e32 v89, v2
	v_mov_b32_e32 v98, v2
	v_mov_b32_e32 v99, v2
	v_mov_b32_e32 v100, v2
	v_mov_b32_e32 v101, v2
	v_mov_b32_e32 v102, v2
	v_mov_b32_e32 v103, v2
	v_mov_b32_e32 v104, v2
	v_mov_b32_e32 v105, v2
	v_mov_b32_e32 v114, v2
	v_mov_b32_e32 v115, v2
	v_mov_b32_e32 v116, v2
	v_mov_b32_e32 v117, v2
	v_mov_b32_e32 v118, v2
	v_mov_b32_e32 v119, v2
	v_mov_b32_e32 v120, v2
	v_mov_b32_e32 v121, v2
	v_mov_b32_e32 v74, v2
	v_mov_b32_e32 v75, v2
	v_mov_b32_e32 v76, v2
	v_mov_b32_e32 v77, v2
	v_mov_b32_e32 v78, v2
	v_mov_b32_e32 v79, v2
	v_mov_b32_e32 v80, v2
	v_mov_b32_e32 v81, v2
	v_mov_b32_e32 v90, v2
	v_mov_b32_e32 v91, v2
	v_mov_b32_e32 v92, v2
	v_mov_b32_e32 v93, v2
	v_mov_b32_e32 v94, v2
	v_mov_b32_e32 v95, v2
	v_mov_b32_e32 v96, v2
	v_mov_b32_e32 v97, v2
	v_mov_b32_e32 v106, v2
	v_mov_b32_e32 v107, v2
	v_mov_b32_e32 v108, v2
	v_mov_b32_e32 v109, v2
	v_mov_b32_e32 v110, v2
	v_mov_b32_e32 v111, v2
	v_mov_b32_e32 v112, v2
	v_mov_b32_e32 v113, v2
	v_mov_b32_e32 v122, v2
	v_mov_b32_e32 v123, v2
	v_mov_b32_e32 v124, v2
	v_mov_b32_e32 v125, v2
	v_mov_b32_e32 v126, v2
	v_mov_b32_e32 v127, v2
	v_mov_b32_e32 v128, v2
	v_mov_b32_e32 v129, v2
	v_add_u32_e32 v141, 0x80, v0
	v_add_u32_e32 v195, 0x80, v130
	v_add_u32_e32 v221, 0x80, v134
	v_add_u32_e32 v223, 0x80, v132
	.p2align	6
